# software prefetch (counted vmcnt double buffer) of the next trip rows in the bf16 rmsnorm loop, phases 4/7/11
# speedup vs baseline: 1.0018x; 1.0018x over previous
; template <bool FINAL, bool SRCB>
; __device__ __forceinline__ void phase_norm(const float* xa, const float* xb, const bfu* xr, const float* w, bfu* dst, float* fdst, const int wv) {
;   const int tid_ = opaque_tid(wv);
;   const int lane = tid_ & 63, wid = tid_ >> 6;
;   f32x4 w4[4];
; #pragma unroll
;   for (int i = 0; i < 4; ++i) w4[i] = ((const f32x4*)w)[i * 64 + lane];
;   for (int row = blockIdx.x * 8 + wid; row < MT / 2; row += gridDim.x * 8) {
;     f32x4 v[2][4];
;     float ss[2] = {0.f, 0.f};
; #pragma unroll
;     for (int h = 0; h < 2; ++h) {
;       const int r = row + h * (MT / 2);
;       if (SRCB) {
; #pragma unroll
;         for (int i = 0; i < 4; ++i) v[h][i] = bf4_to_f32(((const uint2*)(xr + (size_t)r * D))[i * 64 + lane]);
;       } else {
;         const float* x = r < MP ? xa + (size_t)r * D : xb + (size_t)(r - MP) * D;
; #pragma unroll
;         for (int i = 0; i < 4; ++i) v[h][i] = ((const f32x4*)x)[i * 64 + lane];
;       }
;     }
; #pragma unroll
;     for (int h = 0; h < 2; ++h) {
; #pragma unroll
;       for (int i = 0; i < 4; ++i) ss[h] += v[h][i][0] * v[h][i][0] + v[h][i][1] * v[h][i][1] + v[h][i][2] * v[h][i][2] + v[h][i][3] * v[h][i][3];
;       ss[h] = wave_sum(ss[h], lane);
.LBB0_701:
	v_mbcnt_lo_u32_b32 v0, -1, 0
	v_mbcnt_hi_u32_b32 v0, -1, v0
	s_mov_b32 s2, 0x8100
	v_add_u32_e32 v2, s86, v0
	v_ashrrev_i32_e32 v2, 6, v2
	v_add_u32_e32 v18, s95, v2
	v_cmp_gt_i32_e32 vcc, s2, v18
	s_and_saveexec_b64 s[10:11], vcc
	s_mov_b32 s14, 0x3a800000
	s_cbranch_execz .LBB0_704
	v_and_b32_e32 v0, 63, v0
	v_lshlrev_b32_e32 v14, 4, v0
	s_waitcnt lgkmcnt(0)
	global_load_dwordx4 v[2:5], v14, s[8:9]
	global_load_dwordx4 v[6:9], v14, s[8:9] offset:1024
	global_load_dwordx4 v[10:13], v14, s[8:9] offset:2048
	s_nop 0
	global_load_dwordx4 v[14:17], v14, s[8:9] offset:3072
	s_load_dwordx2 s[2:3], s[0:1], 0xe0
	v_lshlrev_b32_e32 v19, 2, v0
	v_lshlrev_b32_e32 v0, 3, v0
	v_xor_b32_e32 v34, 0x80, v19
	v_xor_b32_e32 v35, 64, v19
	s_waitcnt lgkmcnt(0)
	v_lshl_add_u64 v[22:23], s[2:3], 0, v[0:1]
	s_mov_b64 s[2:3], 0x3499c000
	v_lshl_add_u64 v[20:21], v[22:23], 0, s[2:3]
	s_mov_b64 s[2:3], 0x3780000
	v_xor_b32_e32 v36, 32, v19
	v_xor_b32_e32 v37, 16, v19
	v_xor_b32_e32 v38, 8, v19
	v_xor_b32_e32 v39, 4, v19
	v_lshl_add_u64 v[22:23], v[22:23], 0, s[2:3]
	s_mov_b64 s[12:13], 0
	s_load_dword s2, s[54:55], 0x0
	v_ashrrev_i32_e32 v19, 31, v18
	v_lshlrev_b64 v[216:217], 11, v[18:19]
	v_lshl_add_u64 v[220:221], v[20:21], 0, v[216:217]
	global_load_dwordx2 v[200:201], v[220:221], off offset:512
	global_load_dwordx2 v[202:203], v[220:221], off offset:1024
	global_load_dwordx2 v[204:205], v[220:221], off
	global_load_dwordx2 v[206:207], v[220:221], off offset:1536
	s_waitcnt lgkmcnt(0)
	v_lshlrev_b32_e64 v218, 3, s2
	s_mov_b64 s[2:3], 0x4080000
	v_lshl_add_u64 v[216:217], v[216:217], 0, s[2:3]
	v_lshl_add_u64 v[220:221], v[20:21], 0, v[216:217]
	global_load_dwordx2 v[208:209], v[220:221], off offset:512
	global_load_dwordx2 v[210:211], v[220:221], off offset:1024
	global_load_dwordx2 v[212:213], v[220:221], off
	global_load_dwordx2 v[214:215], v[220:221], off offset:1536
	s_waitcnt vmcnt(0)
.LBB0_703:
	v_ashrrev_i32_e32 v19, 31, v18
	v_lshlrev_b64 v[40:41], 11, v[18:19]
	s_mov_b64 s[2:3], 0x4080000
	v_lshl_add_u64 v[24:25], v[40:41], 0, s[2:3]
	v_mov_b64_e32 v[26:27], v[200:201]
	v_mov_b64_e32 v[28:29], v[202:203]
	v_mov_b64_e32 v[30:31], v[204:205]
	v_mov_b64_e32 v[32:33], v[206:207]
	v_mov_b64_e32 v[44:45], v[208:209]
	v_mov_b64_e32 v[46:47], v[210:211]
	v_mov_b64_e32 v[48:49], v[212:213]
	v_mov_b64_e32 v[42:43], v[214:215]
	v_add_u32_e32 v216, v218, v18
	v_cmp_ge_i32_e32 vcc, s51, v216
	s_and_saveexec_b64 vcc, vcc
	v_ashrrev_i32_e32 v217, 31, v216
	v_lshlrev_b64 v[216:217], 11, v[216:217]
	v_lshl_add_u64 v[220:221], v[20:21], 0, v[216:217]
	global_load_dwordx2 v[200:201], v[220:221], off offset:512
	global_load_dwordx2 v[202:203], v[220:221], off offset:1024
	global_load_dwordx2 v[204:205], v[220:221], off
	global_load_dwordx2 v[206:207], v[220:221], off offset:1536
	v_lshl_add_u64 v[216:217], v[216:217], 0, s[2:3]
	v_lshl_add_u64 v[220:221], v[20:21], 0, v[216:217]
	global_load_dwordx2 v[208:209], v[220:221], off offset:512
	global_load_dwordx2 v[210:211], v[220:221], off offset:1024
	global_load_dwordx2 v[212:213], v[220:221], off
	global_load_dwordx2 v[214:215], v[220:221], off offset:1536
	s_mov_b64 exec, vcc
	v_lshl_add_u64 v[40:41], v[22:23], 0, v[40:41]
	v_lshl_add_u64 v[24:25], v[22:23], 0, v[24:25]
	v_and_b32_e32 v53, 0xffff0000, v26
	v_lshlrev_b32_e32 v51, 16, v26
	v_and_b32_e32 v52, 0xffff0000, v30
	v_and_b32_e32 v73, 0xffff0000, v44
	v_lshlrev_b32_e32 v50, 16, v30
	v_and_b32_e32 v72, 0xffff0000, v48
	v_lshlrev_b32_e32 v55, 16, v27
	v_and_b32_e32 v57, 0xffff0000, v27
	v_and_b32_e32 v61, 0xffff0000, v32
	v_and_b32_e32 v60, 0xffff0000, v28
	v_pk_mul_f32 v[66:67], v[52:53], v[52:53]
	v_lshlrev_b32_e32 v71, 16, v44
	v_lshlrev_b32_e32 v70, 16, v48
	v_lshlrev_b32_e32 v74, 16, v49
	v_and_b32_e32 v44, 0xffff0000, v49
	v_and_b32_e32 v27, 0xffff0000, v42
	v_and_b32_e32 v26, 0xffff0000, v46
	v_pk_mul_f32 v[48:49], v[72:73], v[72:73]
	v_lshlrev_b32_e32 v54, 16, v31
	v_and_b32_e32 v56, 0xffff0000, v31
	v_lshlrev_b32_e32 v59, 16, v32
	v_lshlrev_b32_e32 v58, 16, v28
	v_lshlrev_b32_e32 v63, 16, v33
	v_lshlrev_b32_e32 v62, 16, v29
	v_and_b32_e32 v65, 0xffff0000, v33
	v_and_b32_e32 v64, 0xffff0000, v29
	v_pk_mul_f32 v[68:69], v[60:61], v[60:61]
	v_lshlrev_b32_e32 v75, 16, v45
	v_lshlrev_b32_e32 v29, 16, v42
	v_lshlrev_b32_e32 v28, 16, v46
	v_lshlrev_b32_e32 v33, 16, v43
	v_and_b32_e32 v31, 0xffff0000, v43
	v_pk_fma_f32 v[42:43], v[50:51], v[50:51], v[66:67]
	v_pk_mul_f32 v[66:67], v[26:27], v[26:27]
	v_pk_fma_f32 v[48:49], v[70:71], v[70:71], v[48:49]
	v_and_b32_e32 v45, 0xffff0000, v45
	v_lshlrev_b32_e32 v32, 16, v47
	v_and_b32_e32 v30, 0xffff0000, v47
	v_pk_fma_f32 v[46:47], v[58:59], v[58:59], v[68:69]
	v_pk_fma_f32 v[42:43], v[54:55], v[54:55], v[42:43]
	v_pk_fma_f32 v[66:67], v[28:29], v[28:29], v[66:67]
	v_pk_fma_f32 v[48:49], v[74:75], v[74:75], v[48:49]
	v_pk_fma_f32 v[46:47], v[62:63], v[62:63], v[46:47]
	v_pk_fma_f32 v[42:43], v[56:57], v[56:57], v[42:43]
	v_pk_fma_f32 v[66:67], v[32:33], v[32:33], v[66:67]
	v_pk_fma_f32 v[48:49], v[44:45], v[44:45], v[48:49]
	v_pk_fma_f32 v[46:47], v[64:65], v[64:65], v[46:47]
	v_pk_fma_f32 v[66:67], v[30:31], v[30:31], v[66:67]
	v_mov_b32_e32 v69, v42
	v_mov_b32_e32 v68, v48
	v_mov_b32_e32 v42, v49
	v_mov_b32_e32 v77, v46
	v_mov_b32_e32 v76, v66
	v_pk_add_f32 v[42:43], v[68:69], v[42:43]
	v_mov_b32_e32 v46, v67
	v_pk_add_f32 v[42:43], v[42:43], v[76:77]
	v_mov_b32_e32 v48, v50
	v_pk_add_f32 v[42:43], v[42:43], v[46:47]
	ds_bpermute_b32 v47, v34, v43
	ds_bpermute_b32 v46, v34, v42
	v_mov_b32_e32 v49, v52
	v_mov_b32_e32 v66, v54
	v_mov_b32_e32 v67, v56
	v_mov_b32_e32 v52, v51
	s_waitcnt lgkmcnt(0)
; template <bool FINAL, bool SRCB>
; __device__ __forceinline__ void phase_norm(const float* xa, const float* xb, const bfu* xr, const float* w, bfu* dst, float* fdst, const int wv) {
;     ...
; #pragma unroll
;     for (int h = 0; h < 2; ++h) {
; #pragma unroll
;       for (int i = 0; i < 4; ++i) ss[h] += v[h][i][0] * v[h][i][0] + v[h][i][1] * v[h][i][1] + v[h][i][2] * v[h][i][2] + v[h][i][3] * v[h][i][3];
;       ss[h] = wave_sum(ss[h], lane);
;     }
; #pragma unroll
;     for (int h = 0; h < 2; ++h) {
;       const int r = row + h * (MT / 2);
;       const float rstd = rsqrtf(ss[h] * (1.f / D) + EPS);
; #pragma unroll
;       for (int i = 0; i < 4; ++i) {
;         f32x4 o = v[h][i] * rstd * w4[i];
;         if (FINAL) {
;           ((f32x4*)(fdst + (size_t)r * D))[i * 64 + lane] = o;
;         } else {
;           uint2 pk; pk.x = cvt_pk_bf16(o[0], o[1]); pk.y = cvt_pk_bf16(o[2], o[3]);
;           ((uint2*)(dst + (size_t)r * D))[i * 64 + lane] = pk;
;         }
;       }
;     }
;   }
	v_pk_add_f32 v[42:43], v[42:43], v[46:47]
	ds_bpermute_b32 v47, v35, v43
	ds_bpermute_b32 v46, v35, v42
	v_mov_b32_e32 v56, v55
	v_mov_b32_e32 v50, v58
	v_mov_b32_e32 v51, v60
	v_mov_b32_e32 v68, v62
	s_waitcnt lgkmcnt(0)
	v_pk_add_f32 v[42:43], v[42:43], v[46:47]
	ds_bpermute_b32 v47, v36, v43
	ds_bpermute_b32 v46, v36, v42
	v_mov_b32_e32 v69, v64
	v_mov_b32_e32 v60, v59
	v_mov_b32_e32 v64, v63
	v_mov_b32_e32 v58, v70
	s_waitcnt lgkmcnt(0)
	v_pk_add_f32 v[42:43], v[42:43], v[46:47]
	ds_bpermute_b32 v47, v37, v43
	ds_bpermute_b32 v46, v37, v42
	v_mov_b32_e32 v59, v72
	v_mov_b32_e32 v72, v71
	s_waitcnt lgkmcnt(0)
	v_pk_add_f32 v[42:43], v[42:43], v[46:47]
	ds_bpermute_b32 v47, v38, v43
	ds_bpermute_b32 v46, v38, v42
	s_waitcnt lgkmcnt(0)
	v_pk_add_f32 v[42:43], v[42:43], v[46:47]
	ds_bpermute_b32 v47, v39, v43
	ds_bpermute_b32 v46, v39, v42
	s_waitcnt lgkmcnt(0)
	v_pk_add_f32 v[42:43], v[42:43], v[46:47]
	s_nop 0
	v_pk_fma_f32 v[42:43], v[42:43], s[14:15], v[146:147] op_sel_hi:[1,0,0]
	s_nop 0
	v_mul_f32_e32 v0, 0x4b800000, v43
	v_cmp_gt_f32_e32 vcc, s33, v43
	v_mul_f32_e32 v19, 0x4b800000, v42
	v_cmp_gt_f32_e64 s[6:7], s33, v42
	v_cndmask_b32_e32 v0, v43, v0, vcc
	v_rsq_f32_e32 v0, v0
	v_cndmask_b32_e64 v19, v42, v19, s[6:7]
	v_rsq_f32_e32 v19, v19
	v_mul_f32_e32 v42, 0x45800000, v0
	v_cndmask_b32_e32 v0, v0, v42, vcc
	v_pk_mul_f32 v[46:47], v[0:1], v[48:49] op_sel_hi:[0,1]
	v_pk_mul_f32 v[48:49], v[0:1], v[66:67] op_sel_hi:[0,1]
	v_pk_mul_f32 v[46:47], v[2:3], v[46:47]
	v_pk_mul_f32 v[52:53], v[0:1], v[52:53] op_sel_hi:[0,1]
	v_pk_mul_f32 v[54:55], v[0:1], v[56:57] op_sel_hi:[0,1]
	v_pk_mul_f32 v[48:49], v[4:5], v[48:49]
	v_cvt_pk_bf16_f32 v46, v46, v47
	v_pk_mul_f32 v[50:51], v[0:1], v[50:51] op_sel_hi:[0,1]
	v_cvt_pk_bf16_f32 v47, v48, v49
	v_pk_mul_f32 v[56:57], v[0:1], v[68:69] op_sel_hi:[0,1]
	v_pk_mul_f32 v[54:55], v[8:9], v[54:55]
	v_pk_mul_f32 v[52:53], v[6:7], v[52:53]
	global_store_dwordx2 v[40:41], v[46:47], off
	v_cvt_pk_bf16_f32 v46, v52, v53
	v_cvt_pk_bf16_f32 v47, v54, v55
	v_mul_f32_e32 v43, 0x45800000, v19
	v_pk_mul_f32 v[60:61], v[0:1], v[60:61] op_sel_hi:[0,1]
	v_pk_mul_f32 v[62:63], v[0:1], v[64:65] op_sel_hi:[0,1]
	v_pk_mul_f32 v[56:57], v[12:13], v[56:57]
	v_pk_mul_f32 v[50:51], v[10:11], v[50:51]
	global_store_dwordx2 v[40:41], v[46:47], off offset:512
	v_cvt_pk_bf16_f32 v46, v50, v51
	v_cvt_pk_bf16_f32 v47, v56, v57
	v_cndmask_b32_e64 v42, v19, v43, s[6:7]
	v_pk_mul_f32 v[62:63], v[16:17], v[62:63]
	v_pk_mul_f32 v[60:61], v[14:15], v[60:61]
	global_store_dwordx2 v[40:41], v[46:47], off offset:1024
	v_cvt_pk_bf16_f32 v46, v60, v61
	v_cvt_pk_bf16_f32 v47, v62, v63
	global_store_dwordx2 v[40:41], v[46:47], off offset:1536
	v_mov_b32_e32 v40, v74
	v_mov_b32_e32 v41, v44
	v_pk_mul_f32 v[58:59], v[42:43], v[58:59] op_sel_hi:[0,1]
	v_pk_mul_f32 v[40:41], v[42:43], v[40:41] op_sel_hi:[0,1]
	v_pk_mul_f32 v[40:41], v[4:5], v[40:41]
	v_pk_mul_f32 v[46:47], v[2:3], v[58:59]
	v_mov_b32_e32 v44, v75
	v_cvt_pk_bf16_f32 v46, v46, v47
	v_cvt_pk_bf16_f32 v47, v40, v41
	v_pk_mul_f32 v[40:41], v[42:43], v[72:73] op_sel_hi:[0,1]
	v_pk_mul_f32 v[44:45], v[42:43], v[44:45] op_sel_hi:[0,1]
	v_pk_mul_f32 v[40:41], v[6:7], v[40:41]
	global_store_dwordx2 v[24:25], v[46:47], off
	v_pk_mul_f32 v[44:45], v[8:9], v[44:45]
	v_cvt_pk_bf16_f32 v40, v40, v41
	s_nop 0
	v_cvt_pk_bf16_f32 v41, v44, v45
	global_store_dwordx2 v[24:25], v[40:41], off offset:512
	v_mov_b32_e32 v40, v28
	v_mov_b32_e32 v41, v26
	v_mov_b32_e32 v26, v29
	v_pk_mul_f32 v[40:41], v[42:43], v[40:41] op_sel_hi:[0,1]
	v_mov_b32_e32 v44, v32
	v_mov_b32_e32 v45, v30
	v_pk_mul_f32 v[26:27], v[42:43], v[26:27] op_sel_hi:[0,1]
	v_mov_b32_e32 v30, v33
	v_pk_mul_f32 v[44:45], v[42:43], v[44:45] op_sel_hi:[0,1]
	v_pk_mul_f32 v[40:41], v[10:11], v[40:41]
	v_pk_mul_f32 v[28:29], v[42:43], v[30:31] op_sel_hi:[0,1]
	v_pk_mul_f32 v[26:27], v[14:15], v[26:27]
	v_pk_mul_f32 v[44:45], v[12:13], v[44:45]
	v_cvt_pk_bf16_f32 v40, v40, v41
	v_pk_mul_f32 v[28:29], v[16:17], v[28:29]
	v_cvt_pk_bf16_f32 v41, v44, v45
	global_store_dwordx2 v[24:25], v[40:41], off offset:1024
	v_cvt_pk_bf16_f32 v26, v26, v27
	v_cvt_pk_bf16_f32 v27, v28, v29
	global_store_dwordx2 v[24:25], v[26:27], off offset:1536
	s_load_dword s2, s[54:55], 0x0
	s_waitcnt lgkmcnt(0)
	v_lshl_add_u32 v18, s2, 3, v18
	v_cmp_lt_i32_e32 vcc, s51, v18
	s_or_b64 s[12:13], vcc, s[12:13]
	s_waitcnt vmcnt(8)
	s_andn2_b64 exec, exec, s[12:13]
	s_cbranch_execnz .LBB0_703
